# remaining grid barrier: L1 invalidate issued before the wait (overlaps polling / L2 write-back); census adds poison XCC ids above 7
# speedup vs baseline: 1.0016x; 1.0016x over previous
; #define LAS __attribute__((address_space(3)))
; __device__ __forceinline__ unsigned xb_ld(unsigned* p)              { return __hip_atomic_load(p, __ATOMIC_RELAXED, __HIP_MEMORY_SCOPE_AGENT); }
; __device__ __forceinline__ unsigned xb_add(unsigned* p, unsigned v) { return __hip_atomic_fetch_add(p, v, __ATOMIC_RELAXED, __HIP_MEMORY_SCOPE_AGENT); }
; __device__ __forceinline__ unsigned xb_xcc_id() { return (unsigned)__builtin_amdgcn_s_getreg((3 << 11) | 20) & 0xFu; }
; #define XB_SPIN(cond, bar) do { unsigned _sp = 0; while (cond) { __builtin_amdgcn_s_sleep(1); \
;     if ((++_sp & 255u) == 0u) { if (xb_ld(&(bar)[XB_TMO])) break; if (_sp > XB_SPIN_CAP) { atomicAdd(&(bar)[XB_TMO], 1u); break; } } } } while (0)
; __device__ __forceinline__ XcdBarrier xcd_barrier_post(unsigned* bar, volatile LAS unsigned* st) {
;     XcdBarrier b; b.bar = bar; b.x = xb_xcc_id(); b.st = st;
;     if (threadIdx.x == 0) (void)xb_add(&bar[XB_XCNT(b.x)], 1u);
;     return b;
; }
; __device__ __forceinline__ void xcd_barrier(const XcdBarrier& b) {
;     asm volatile("s_waitcnt vmcnt(0)" ::: "memory");
;     __syncthreads();
;     if (threadIdx.x == 0) {
;         unsigned* bar = b.bar;
;         __builtin_amdgcn_s_waitcnt(0);
;         unsigned nloc = b.st[0], nx = b.st[1];
;         if (nloc == 0u) { xcd_barrier_complete(bar, b.x, nloc, nx); b.st[0] = nloc; b.st[1] = nx; }
;         const unsigned old = xb_add(&bar[XB_XSUB(b.x)], 1u);
;         const unsigned gen = old / nloc;
;         if (old + 1u == (gen + 1u) * nloc) {
;             __builtin_amdgcn_fence(__ATOMIC_RELEASE, "agent");
;             asm volatile("s_waitcnt vmcnt(0)" ::: "memory");
;             const unsigned og = xb_add(&bar[XB_TOP], 1u);
;             const unsigned tg = og / nx;
;             if (og + 1u == (tg + 1u) * nx) xb_add(&bar[XB_TOPGEN], 1u);
;             else XB_SPIN(xb_ld(&bar[XB_TOPGEN]) == tg, bar);
.LBB0_101:
	s_cmp_lt_i32 s19, 2
	s_cbranch_scc1 .LBB0_155
	s_waitcnt vmcnt(0)
	s_waitcnt lgkmcnt(0)
	s_barrier
	s_mov_b64 s[0:1], exec
	v_readlane_b32 s2, v247, 37
	v_readlane_b32 s3, v247, 38
	s_and_b64 s[2:3], s[0:1], s[2:3]
	s_mov_b64 exec, s[2:3]
	s_cbranch_execz .LBB0_154
	v_readlane_b32 s4, v247, 36
	s_nop 0
	s_and_b32 s2, s4, 7
	s_lshl_b32 s2, s2, 2
	s_cmp_gt_u32 s4, 7
	s_cselect_b32 s3, 7, 1
	s_lshl_b32 s3, s3, s2
	v_mov_b32_e32 v2, s3
	s_and_b32 s2, s90, 31
	s_lshl_b32 s2, s2, 6
	s_add_u32 s2, s62, s2
	s_addc_u32 s3, s63, 0
	s_add_u32 s2, s2, 0xa000
	s_addc_u32 s3, s3, 0
	v_mov_b32_e32 v1, 0
	global_atomic_add v1, v2, s[2:3]
	s_and_b32 s2, s4, 3
	s_lshl_b32 s2, s2, 3
	s_cmp_gt_u32 s4, 7
	s_cselect_b32 s3, 33, 1
	s_lshl_b32 s3, s3, s2
	v_mov_b32_e32 v2, s3
	s_and_b32 s2, s90, 7
	s_lshl_b32 s2, s2, 7
	s_lshr_b32 s3, s4, 2
	s_and_b32 s3, s3, 1
	s_lshl_b32 s3, s3, 6
	s_add_i32 s2, s2, s3
	s_add_u32 s2, s62, s2
	s_addc_u32 s3, s63, 0
	s_add_u32 s2, s2, 0xa800
	s_addc_u32 s3, s3, 0
	global_atomic_add v1, v2, s[2:3]
	s_add_i32 s2, 0, 0x24160
	v_mov_b32_e32 v1, s2
	s_waitcnt vmcnt(0) expcnt(0) lgkmcnt(0)
	ds_read_b32 v3, v1
	s_add_i32 s2, 0, 0x24164
	v_mov_b32_e32 v1, s2
	ds_read_b32 v1, v1
	s_waitcnt lgkmcnt(1)
	v_cmp_ne_u32_e32 vcc, 0, v3
	s_cbranch_vccnz .LBB0_118
	v_readlane_b32 s2, v247, 0
	v_readlane_b32 s3, v247, 1
	s_load_dwordx2 s[6:7], s[2:3], 0x4
	s_add_u32 s2, s62, 0x4200
	s_addc_u32 s3, s63, 0
	s_add_u32 s4, s62, 0x4400
	s_addc_u32 s5, s63, 0
	s_waitcnt lgkmcnt(0)
	s_mul_i32 s33, s6, s80
	s_add_u32 s6, s62, 0x4500
	s_mul_i32 s33, s33, s7
	s_addc_u32 s7, s63, 0
	s_add_u32 s8, s62, 0x4600
	s_addc_u32 s9, s63, 0
	s_add_u32 s10, s62, 0x4700
	s_addc_u32 s11, s63, 0
	s_add_u32 s12, s62, 0x4800
	s_addc_u32 s13, s63, 0
	s_add_u32 s14, s62, 0x4900
	s_addc_u32 s15, s63, 0
	s_add_u32 s16, s62, 0x4a00
	s_addc_u32 s17, s63, 0
	s_add_u32 s18, s62, 0x4b00
	s_addc_u32 s19, s63, 0
	s_add_u32 s20, s62, 0x4c00
	s_addc_u32 s21, s63, 0
	s_add_u32 s24, s62, 0x4d00
	s_addc_u32 s25, s63, 0
	s_add_u32 s26, s62, 0x4e00
	s_addc_u32 s27, s63, 0
	s_add_u32 s28, s62, 0x4f00
	s_addc_u32 s29, s63, 0
	s_add_u32 s30, s62, 0x5000
	s_addc_u32 s31, s63, 0
	s_add_u32 s34, s62, 0x5100
	s_addc_u32 s35, s63, 0
	s_add_u32 s36, s62, 0x5200
	s_addc_u32 s37, s63, 0
	s_add_u32 s38, s62, 0x5300
	s_addc_u32 s39, s63, 0
	s_mov_b32 s48, 1
	v_mov_b32_e32 v17, 0
	s_branch .LBB0_106

; __device__ __forceinline__ unsigned xb_ld(unsigned* p)              { return __hip_atomic_load(p, __ATOMIC_RELAXED, __HIP_MEMORY_SCOPE_AGENT); }
; __device__ __forceinline__ unsigned xb_add(unsigned* p, unsigned v) { return __hip_atomic_fetch_add(p, v, __ATOMIC_RELAXED, __HIP_MEMORY_SCOPE_AGENT); }
; #define XB_SPIN(cond, bar) do { unsigned _sp = 0; while (cond) { __builtin_amdgcn_s_sleep(1); \
;     if ((++_sp & 255u) == 0u) { if (xb_ld(&(bar)[XB_TMO])) break; if (_sp > XB_SPIN_CAP) { atomicAdd(&(bar)[XB_TMO], 1u); break; } } } } while (0)
; __device__ __forceinline__ void xcd_barrier(const XcdBarrier& b) {
;     ...
;         const unsigned old = xb_add(&bar[XB_XSUB(b.x)], 1u);
;         const unsigned gen = old / nloc;
;         if (old + 1u == (gen + 1u) * nloc) {
;             __builtin_amdgcn_fence(__ATOMIC_RELEASE, "agent");
;             asm volatile("s_waitcnt vmcnt(0)" ::: "memory");
;             const unsigned og = xb_add(&bar[XB_TOP], 1u);
;             const unsigned tg = og / nx;
;             if (og + 1u == (tg + 1u) * nx) xb_add(&bar[XB_TOPGEN], 1u);
;             else XB_SPIN(xb_ld(&bar[XB_TOPGEN]) == tg, bar);
.LBB0_120:
	s_or_b64 exec, exec, s[6:7]
	v_cvt_f32_u32_e32 v5, v3
	s_waitcnt vmcnt(0)
	v_readfirstlane_b32 s4, v4
	v_sub_u32_e32 v4, 0, v3
	v_rcp_iflag_f32_e32 v5, v5
	v_add_u32_e32 v6, s4, v2
	v_mul_f32_e32 v5, 0x4f7ffffe, v5
	v_cvt_u32_f32_e32 v5, v5
	v_mul_lo_u32 v2, v4, v5
	v_mul_hi_u32 v2, v5, v2
	v_add_u32_e32 v2, v5, v2
	v_mul_hi_u32 v2, v6, v2
	v_mul_lo_u32 v4, v2, v3
	v_sub_u32_e32 v4, v6, v4
	v_add_u32_e32 v5, 1, v2
	v_cmp_ge_u32_e32 vcc, v4, v3
	s_nop 1
	v_cndmask_b32_e32 v2, v2, v5, vcc
	v_sub_u32_e32 v5, v4, v3
	v_cndmask_b32_e32 v4, v4, v5, vcc
	v_add_u32_e32 v5, 1, v2
	v_cmp_ge_u32_e32 vcc, v4, v3
	v_add_u32_e32 v4, 1, v6
	s_nop 0
	v_cndmask_b32_e32 v2, v2, v5, vcc
	v_mul_lo_u32 v5, v3, v2
	v_add_u32_e32 v3, v5, v3
	v_cmp_ne_u32_e32 vcc, v4, v3
	s_and_saveexec_b64 s[4:5], vcc
	s_xor_b64 s[4:5], exec, s[4:5]
	s_cbranch_execz .LBB0_134
	s_waitcnt lgkmcnt(0)
	s_add_u32 s10, s62, 0x7500
	s_addc_u32 s11, s63, 0
	v_mov_b32_e32 v1, 0
	buffer_inv sc1
	global_load_dword v1, v1, s[10:11] sc1
	s_waitcnt vmcnt(0)
	v_cmp_eq_u32_e32 vcc, v1, v2
	s_and_saveexec_b64 s[6:7], vcc
	s_cbranch_execz .LBB0_133
	s_add_u32 s8, s62, 0x4200
	s_addc_u32 s9, s63, 0
	s_mov_b32 s24, 1
	s_mov_b64 s[12:13], 0
	v_mov_b32_e32 v1, 0
	s_branch .LBB0_124

; __device__ __forceinline__ unsigned xb_add(unsigned* p, unsigned v) { return __hip_atomic_fetch_add(p, v, __ATOMIC_RELAXED, __HIP_MEMORY_SCOPE_AGENT); }
; __device__ __forceinline__ void xcd_barrier(const XcdBarrier& b) {
;     ...
;         if (old + 1u == (gen + 1u) * nloc) {
;             __builtin_amdgcn_fence(__ATOMIC_RELEASE, "agent");
;             asm volatile("s_waitcnt vmcnt(0)" ::: "memory");
;             const unsigned og = xb_add(&bar[XB_TOP], 1u);
;             const unsigned tg = og / nx;
;             if (og + 1u == (tg + 1u) * nx) xb_add(&bar[XB_TOPGEN], 1u);
.LBB0_133:
	s_or_b64 exec, exec, s[6:7]
	s_waitcnt vmcnt(0)
	s_waitcnt vmcnt(0)
.LBB0_134:
	s_andn2_saveexec_b64 s[4:5], s[4:5]
	s_cbranch_execz .LBB0_154
	s_mov_b64 s[4:5], exec
	buffer_wbl2 sc1
	buffer_inv sc1
	s_waitcnt lgkmcnt(0)
	s_waitcnt vmcnt(0)
	v_mbcnt_lo_u32_b32 v2, s4, 0
	v_mbcnt_hi_u32_b32 v2, s5, v2
	v_cmp_eq_u32_e32 vcc, 0, v2
	s_and_saveexec_b64 s[6:7], vcc
	s_cbranch_execz .LBB0_137
	s_bcnt1_i32_b64 s4, s[4:5]
	v_mov_b32_e32 v3, 0x7000
	v_mov_b32_e32 v4, s4
	global_atomic_add v3, v3, v4, s[62:63] offset:1024 sc0

; __device__ __forceinline__ unsigned xb_add(unsigned* p, unsigned v) { return __hip_atomic_fetch_add(p, v, __ATOMIC_RELAXED, __HIP_MEMORY_SCOPE_AGENT); }
; __device__ __forceinline__ void xcd_barrier(const XcdBarrier& b) {
;     ...
;             __builtin_amdgcn_fence(__ATOMIC_ACQUIRE, "agent");
;             xb_add(&bar[XB_XGEN(b.x)], 1u);
;             asm volatile("s_waitcnt vmcnt(0)" ::: "memory");
.LBB0_151:
	s_or_b64 exec, exec, s[4:5]
	s_mov_b64 s[4:5], exec
	v_mbcnt_lo_u32_b32 v1, s4, 0
	v_mbcnt_hi_u32_b32 v1, s5, v1
	v_cmp_eq_u32_e32 vcc, 0, v1
	s_waitcnt vmcnt(0)
	s_and_saveexec_b64 s[6:7], vcc
	s_cbranch_execz .LBB0_153
	s_bcnt1_i32_b64 s4, s[4:5]
	v_mov_b32_e32 v1, 0x2000
	v_mov_b32_e32 v2, s4
	global_atomic_add v1, v2, s[2:3] offset:1024
